# attention exp/PV phase: the 7 remaining v_pk_add_f32 split into scalar v_add_f32 pairs (same values), on the load-segment priority version
# speedup vs baseline: 1.0074x; 1.0074x over previous
.LBB0_1801:
	v_exp_f32_e32 v188, v66
	v_exp_f32_e32 v189, v50
	v_exp_f32_e32 v0, v67
	v_exp_f32_e32 v50, v51
	v_exp_f32_e32 v190, v52
	v_add_f32_e32 v51, v189, v188
	v_exp_f32_e32 v80, v80
	v_add_f32_e32 v66, v50, v0
	v_add_f32_e32 v67, v51, v1
	v_exp_f32_e32 v51, v68
	v_add_f32_e32 v67, v66, v67
	v_exp_f32_e32 v66, v69
	v_exp_f32_e32 v68, v53
	v_add_f32_e32 v69, v190, v51
	v_cvt_pk_bf16_f32 v50, v189, v50
	v_add_f32_e32 v52, v68, v66
	v_add_f32_e32 v53, v69, v67
	s_nop 0
	v_add_f32_e32 v179, v52, v53
	v_exp_f32_e32 v67, v70
	v_exp_f32_e32 v69, v54
	v_exp_f32_e32 v178, v71
	v_exp_f32_e32 v70, v55
	v_exp_f32_e32 v55, v72
	v_add_f32_e32 v71, v69, v67
	v_exp_f32_e32 v72, v57
	v_add_f32_e32 v52, v70, v178
	v_add_f32_e32 v53, v71, v179
	v_exp_f32_e32 v71, v56
	v_add_f32_e32 v181, v52, v53
	v_exp_f32_e32 v180, v73
	v_exp_f32_e32 v179, v58
	v_add_f32_e32 v73, v71, v55
	v_cvt_pk_bf16_f32 v54, v67, v178
	v_add_f32_e32 v52, v72, v180
	v_add_f32_e32 v53, v73, v181
	v_exp_f32_e32 v73, v74
	v_add_f32_e32 v183, v52, v53
	v_exp_f32_e32 v182, v75
	v_exp_f32_e32 v74, v59
	v_add_f32_e32 v75, v179, v73
	v_exp_f32_e32 v181, v60
	v_cvt_pk_bf16_f32 v55, v55, v180
	v_add_f32_e32 v52, v74, v182
	v_add_f32_e32 v53, v75, v183
	v_exp_f32_e32 v75, v76
	v_add_f32_e32 v185, v52, v53
	v_exp_f32_e32 v184, v77
	v_exp_f32_e32 v76, v61
	v_add_f32_e32 v77, v181, v75
	v_exp_f32_e32 v183, v62
	v_add3_u32 v62, s56, v208, v120
	v_add_f32_e32 v52, v76, v184
	v_add_f32_e32 v53, v77, v185
	v_exp_f32_e32 v77, v78
	v_add_f32_e32 v187, v52, v53
	v_cvt_pk_bf16_f32 v52, v188, v0
	v_add_u32_e32 v0, 0x3000, v62
	v_cvt_pk_bf16_f32 v53, v51, v66
	ds_read2_b64 v[56:59], v0 offset0:128 offset1:130
	v_exp_f32_e32 v186, v79
	v_exp_f32_e32 v66, v63
	v_add_f32_e32 v67, v183, v77
	s_waitcnt lgkmcnt(0)
	v_mfma_f32_32x32x16_bf16 v[18:33], v[52:55], v[56:59], v[18:33]
	v_add_f32_e64 v60, v66, v186
	v_add_f32_e64 v61, v67, v187
	v_add_u32_e32 v67, 0x4000, v62
	ds_read2_b64 v[56:59], v67 offset0:192 offset1:194
	v_add_f32_e64 v79, v60, v61
	v_exp_f32_e32 v78, v81
	ds_read2_b64 v[60:63], v0 offset0:132 offset1:134
	v_cvt_pk_bf16_f32 v51, v190, v68
	s_waitcnt lgkmcnt(1)
	v_mfma_f32_32x32x16_bf16 v[2:17], v[52:55], v[56:59], v[2:17]
	v_cvt_pk_bf16_f32 v52, v73, v182
	v_cvt_pk_bf16_f32 v53, v75, v184
	v_cvt_pk_bf16_f32 v54, v77, v186
	v_cvt_pk_bf16_f32 v55, v80, v78
	ds_read2_b64 v[56:59], v67 offset0:196 offset1:198
	s_waitcnt lgkmcnt(1)
	v_mfma_f32_32x32x16_bf16 v[18:33], v[52:55], v[60:63], v[18:33]
	s_waitcnt lgkmcnt(0)
	v_mfma_f32_32x32x16_bf16 v[2:17], v[52:55], v[56:59], v[2:17]
	v_cvt_pk_bf16_f32 v52, v69, v70
	v_cvt_pk_bf16_f32 v53, v71, v72
	ds_read2_b64 v[54:57], v0 offset0:136 offset1:138
	v_exp_f32_e32 v59, v64
	v_exp_f32_e32 v58, v65
	s_waitcnt lgkmcnt(0)
	v_mfma_f32_32x32x16_bf16 v[18:33], v[50:53], v[54:57], v[18:33]
	ds_read2_b64 v[54:57], v67 offset0:200 offset1:202
	s_waitcnt lgkmcnt(0)
	v_mfma_f32_32x32x16_bf16 v[2:17], v[50:53], v[54:57], v[2:17]
	v_cvt_pk_bf16_f32 v50, v179, v74
	v_cvt_pk_bf16_f32 v51, v181, v76
	v_cvt_pk_bf16_f32 v52, v183, v66
	v_cvt_pk_bf16_f32 v53, v59, v58
	ds_read2_b64 v[54:57], v0 offset0:140 offset1:142
	v_add_f32_e32 v59, v59, v80
	v_add_f32_e32 v58, v58, v78
	v_add_f32_e32 v59, v59, v79
	s_waitcnt lgkmcnt(0)
	v_mfma_f32_32x32x16_bf16 v[18:33], v[50:53], v[54:57], v[18:33]
	ds_read2_b64 v[54:57], v67 offset0:204 offset1:206
	v_add_f32_e32 v0, v58, v59
	v_add_f32_e32 v224, v224, v0
	s_waitcnt lgkmcnt(0)
	v_mfma_f32_32x32x16_bf16 v[2:17], v[50:53], v[54:57], v[2:17]
	s_andn2_b64 vcc, exec, s[8:9]
	s_cbranch_vccnz .LBB0_1790
